# attention loop head: wave-uniform any-lane test via s_cmp on the v_cmp mask (ballot trim); ropev: V loads issued together with the K/cos/sin loads
# baseline (speedup 1.0000x reference)
; #define LAS __attribute__((address_space(3)))
; DI void ropev_item(const Params& p, int item, LAS unsigned char* lds, int tid) {
;     ...
;     {
;         const int tok = tid >> 3, ch = tid & 7, t = tile * 64 + tok;
;         bf16_t* kp = proj + (size_t)(b * T + t) * NINP + (which ? C_KW : C_KS) + g * 128 + ch * 8;
;         const u32x4 lo = *(const u32x4*)kp, hi = *(const u32x4*)(kp + 64);
;         const f32x4 c0 = *(const f32x4*)(cosT + t * 64 + ch * 8), c1 = *(const f32x4*)(cosT + t * 64 + ch * 8 + 4);
;         const f32x4 s0 = *(const f32x4*)(sinT + t * 64 + ch * 8), s1 = *(const f32x4*)(sinT + t * 64 + ch * 8 + 4);
;         const float x1[8] = {bflo(lo.x), bfhi(lo.x), bflo(lo.y), bfhi(lo.y), bflo(lo.z), bfhi(lo.z), bflo(lo.w), bfhi(lo.w)};
;         const float x2[8] = {bflo(hi.x), bfhi(hi.x), bflo(hi.y), bfhi(hi.y), bflo(hi.z), bfhi(hi.z), bflo(hi.w), bfhi(hi.w)};
;         const float cc[8] = {c0.x, c0.y, c0.z, c0.w, c1.x, c1.y, c1.z, c1.w}, ss[8] = {s0.x, s0.y, s0.z, s0.w, s1.x, s1.y, s1.z, s1.w};
;         float y1[8], y2[8];
; #pragma unroll
;         for (int e = 0; e < 8; ++e) { y1[e] = x1[e] * cc[e] - x2[e] * ss[e]; y2[e] = x2[e] * cc[e] + x1[e] * ss[e]; }
;         u32x4 o1, o2; o1.x = pk2(y1[0], y1[1]); o1.y = pk2(y1[2], y1[3]); o1.z = pk2(y1[4], y1[5]); o1.w = pk2(y1[6], y1[7]);
;         o2.x = pk2(y2[0], y2[1]); o2.y = pk2(y2[2], y2[3]); o2.z = pk2(y2[4], y2[5]); o2.w = pk2(y2[6], y2[7]);
;         *(u32x4*)kp = o1; *(u32x4*)(kp + 64) = o2;
;     }
;     LAS bf16_t* Tl = (LAS bf16_t*)lds;
;     u32x4 vreg[2];
; #pragma unroll
;     for (int i = 0; i < 2; ++i) { const int tok = (tid >> 4) + 32 * i, ch = tid & 15;
;         vreg[i] = *(const u32x4*)(proj + (size_t)(b * T + tile * 64 + tok) * NINP + (which ? C_VW : C_VS) + g * 128 + ch * 8); }
;     __builtin_amdgcn_sched_barrier(0);
; #pragma unroll
;     for (int i = 0; i < 2; ++i) { const int tok = (tid >> 4) + 32 * i, ch = tid & 15; const u32x4 v = vreg[i];
;         LAS unsigned* d = (LAS unsigned*)(Tl + tok * 130 + ch * 8); d[0] = v.x; d[1] = v.y; d[2] = v.z; d[3] = v.w; }
;     __syncthreads();
;     {
;         const int d = tid >> 2, tq = tid & 3;
;         unsigned o[8];
; #pragma unroll
;         for (int e = 0; e < 8; ++e) { const unsigned a = Tl[(tq * 16 + 2 * e) * 130 + d], bb = Tl[(tq * 16 + 2 * e + 1) * 130 + d]; o[e] = a | (bb << 16); }
.LBB0_291:
	s_add_i32 s4, s88, s2
	s_mov_b64 s[6:7], s[28:29]
	v_mbcnt_lo_u32_b32 v0, -1, 0
	v_mbcnt_hi_u32_b32 v0, -1, v0
	s_ashr_i32 s4, s4, 8
	v_add_u32_e32 v1, s33, v0
	s_add_u32 s6, s6, 0x1be00000
	v_ashrrev_i32_e32 v2, 3, v1
	s_addc_u32 s7, s7, 0
	v_add_u32_e32 v10, s16, v2
	s_lshl_b32 s5, s4, 12
	v_add_u32_e32 v4, s5, v10
	v_mov_b64_e32 v[2:3], s[6:7]
	v_mad_i64_i32 v[2:3], s[14:15], v4, s96, v[2:3]
	s_mov_b32 s25, s85
	v_lshlrev_b32_e32 v4, 3, v1
	v_lshlrev_b32_e32 v10, 6, v10
	v_lshl_add_u64 v[2:3], v[2:3], 0, s[24:25]
	s_mov_b32 s55, s85
	v_and_b32_e32 v12, 56, v4
	v_ashrrev_i32_e32 v11, 31, v10
	s_mov_b64 s[8:9], s[28:29]
	v_lshl_add_u64 v[2:3], v[2:3], 0, s[54:55]
	v_lshlrev_b32_e32 v198, 1, v12
	v_lshlrev_b64 v[18:19], 2, v[10:11]
	v_lshl_add_u64 v[26:27], v[2:3], 0, v[198:199]
	v_lshl_add_u64 v[10:11], s[8:9], 0, v[18:19]
	v_lshlrev_b32_e32 v198, 2, v12
	s_mov_b64 s[10:11], s[28:29]
	v_lshl_add_u64 v[10:11], v[10:11], 0, v[198:199]
	v_lshl_add_u64 v[14:15], v[10:11], 0, s[56:57]
	v_add_co_u32_e32 v10, vcc, s21, v10
	v_lshl_add_u64 v[18:19], s[10:11], 0, v[18:19]
	s_nop 0
	v_addc_co_u32_e32 v11, vcc, 0, v11, vcc
	v_lshl_add_u64 v[18:19], v[18:19], 0, v[198:199]
	global_load_dwordx4 v[2:5], v[26:27], off
	global_load_dwordx4 v[6:9], v[26:27], off offset:128
	v_lshl_add_u64 v[22:23], v[18:19], 0, s[62:63]
	v_add_co_u32_e32 v18, vcc, s22, v18
	global_load_dwordx4 v[10:13], v[10:11], off
	s_nop 0
	global_load_dwordx4 v[14:17], v[14:15], off offset:16
	v_addc_co_u32_e32 v19, vcc, 0, v19, vcc
	global_load_dwordx4 v[18:21], v[18:19], off
	s_nop 0
	global_load_dwordx4 v[22:25], v[22:23], off offset:16
	s_or_b32 s5, s5, s16
	v_ashrrev_i32_e32 v48, 4, v1
	v_lshlrev_b32_e32 v42, 4, v1
	v_add_u32_e32 v43, s5, v48
	s_add_u32 s5, s6, s20
	s_addc_u32 s7, s7, 0
	s_add_u32 s6, s5, s54
	s_addc_u32 s7, s7, 0
	v_and_b32_e32 v198, 0xf0, v42
	v_lshl_add_u64 v[44:45], s[6:7], 0, v[198:199]
	v_mad_i64_i32 v[46:47], s[6:7], v43, s96, v[44:45]
	v_add_u32_e32 v43, 32, v43
	v_mad_i64_i32 v[44:45], s[6:7], v43, s96, v[44:45]
	global_load_dwordx4 v[34:37], v[46:47], off
	s_nop 0
	global_load_dwordx4 v[38:41], v[44:45], off
	s_waitcnt vmcnt(7)
	v_lshlrev_b32_e32 v28, 16, v2
	v_and_b32_e32 v29, 0xffff0000, v2
	s_waitcnt vmcnt(6)
	v_lshlrev_b32_e32 v30, 16, v6
	v_and_b32_e32 v31, 0xffff0000, v6
	v_lshlrev_b32_e32 v6, 16, v7
	v_and_b32_e32 v7, 0xffff0000, v7
	v_lshlrev_b32_e32 v2, 16, v3
	s_waitcnt vmcnt(3)
	v_pk_mul_f32 v[32:33], v[18:19], v[30:31]
	v_pk_mul_f32 v[18:19], v[18:19], v[28:29]
	v_pk_fma_f32 v[32:33], v[10:11], v[28:29], v[32:33] neg_lo:[0,0,1] neg_hi:[0,0,1]
	v_pk_fma_f32 v[10:11], v[10:11], v[30:31], v[18:19]
	v_and_b32_e32 v3, 0xffff0000, v3
	v_pk_mul_f32 v[18:19], v[20:21], v[6:7]
	s_nop 0
	v_pk_fma_f32 v[18:19], v[12:13], v[2:3], v[18:19] neg_lo:[0,0,1] neg_hi:[0,0,1]
	v_pk_mul_f32 v[2:3], v[20:21], v[2:3]
	s_nop 0
	v_pk_fma_f32 v[12:13], v[12:13], v[6:7], v[2:3]
	v_lshlrev_b32_e32 v6, 16, v8
	v_and_b32_e32 v7, 0xffff0000, v8
	v_lshlrev_b32_e32 v2, 16, v4
	v_and_b32_e32 v3, 0xffff0000, v4
	s_waitcnt vmcnt(2)
	v_pk_mul_f32 v[20:21], v[22:23], v[6:7]
	v_lshlrev_b32_e32 v4, 16, v9
	v_pk_fma_f32 v[20:21], v[14:15], v[2:3], v[20:21] neg_lo:[0,0,1] neg_hi:[0,0,1]
	v_pk_mul_f32 v[2:3], v[22:23], v[2:3]
	s_nop 0
	v_pk_fma_f32 v[14:15], v[14:15], v[6:7], v[2:3]
	v_lshlrev_b32_e32 v2, 16, v5
	v_and_b32_e32 v3, 0xffff0000, v5
	v_and_b32_e32 v5, 0xffff0000, v9
	v_pk_mul_f32 v[6:7], v[24:25], v[4:5]
	v_cvt_pk_bf16_f32 v8, v14, v15
	v_pk_fma_f32 v[6:7], v[16:17], v[2:3], v[6:7] neg_lo:[0,0,1] neg_hi:[0,0,1]
	v_pk_mul_f32 v[2:3], v[24:25], v[2:3]
	s_nop 0
	v_pk_fma_f32 v[16:17], v[16:17], v[4:5], v[2:3]
	v_cvt_pk_bf16_f32 v2, v32, v33
	v_cvt_pk_bf16_f32 v3, v18, v19
	v_cvt_pk_bf16_f32 v4, v20, v21
	v_cvt_pk_bf16_f32 v5, v6, v7
	v_cvt_pk_bf16_f32 v6, v10, v11
	v_ashrrev_i32_e32 v10, 4, v1
	v_cvt_pk_bf16_f32 v7, v12, v13
	v_cvt_pk_bf16_f32 v9, v16, v17
	global_store_dwordx4 v[26:27], v[2:5], off
	global_store_dwordx4 v[26:27], v[6:9], off offset:128
	s_nop 0
	v_mul_lo_u32 v10, v10, s23
	v_add3_u32 v10, 0, v198, v10
	s_waitcnt vmcnt(3)
	ds_write2_b32 v10, v34, v35 offset1:1
	ds_write2_b32 v10, v36, v37 offset0:2 offset1:3
	v_add_u32_e32 v2, 0x2080, v10
	s_waitcnt vmcnt(2)
	ds_write2_b32 v2, v38, v39 offset1:1
	v_add_u32_e32 v2, 0x2088, v10
	v_lshlrev_b32_e32 v0, 4, v0
	ds_write2_b32 v2, v40, v41 offset1:1
	v_ashrrev_i32_e32 v8, 2, v1
	v_and_b32_e32 v10, 48, v0
	v_mul_u32_u24_e32 v0, 0x104, v10
	v_lshlrev_b32_e32 v1, 1, v8
	v_add3_u32 v7, 0, v0, v1
	s_waitcnt lgkmcnt(0)
	s_barrier
	ds_read_u16 v0, v7
	ds_read_u16 v1, v7 offset:260
	s_lshl_b32 s4, s4, 2
	s_or_b32 s4, s4, s17
	s_ashr_i32 s5, s4, 31
	s_mov_b64 s[6:7], s[28:29]
	s_waitcnt lgkmcnt(0)
	v_lshl_or_b32 v0, v1, 16, v0
	ds_read_u16 v1, v7 offset:520
	ds_read_u16 v2, v7 offset:780
	s_lshl_b64 s[4:5], s[4:5], 20
	v_lshlrev_b32_e32 v198, 1, v10
	s_waitcnt lgkmcnt(0)
	v_lshl_or_b32 v1, v2, 16, v1
	ds_read_u16 v2, v7 offset:1040
	ds_read_u16 v3, v7 offset:1300
	s_waitcnt lgkmcnt(0)
	v_lshl_or_b32 v2, v3, 16, v2
	ds_read_u16 v3, v7 offset:1560
	ds_read_u16 v4, v7 offset:1820
	s_waitcnt lgkmcnt(0)
	v_lshl_or_b32 v3, v4, 16, v3
	ds_read_u16 v4, v7 offset:2080
	ds_read_u16 v5, v7 offset:2340
	s_waitcnt lgkmcnt(0)
	v_lshl_or_b32 v4, v5, 16, v4
	ds_read_u16 v5, v7 offset:2600
	ds_read_u16 v6, v7 offset:2860
	s_waitcnt lgkmcnt(0)
	v_lshl_or_b32 v5, v6, 16, v5
	ds_read_u16 v6, v7 offset:3120
	ds_read_u16 v9, v7 offset:3380
	s_waitcnt lgkmcnt(0)
	v_lshl_or_b32 v6, v9, 16, v6
	ds_read_u16 v9, v7 offset:3640
	ds_read_u16 v7, v7 offset:3900
	s_add_u32 s4, s6, s4
	s_addc_u32 s5, s7, s5
	s_addk_i32 s2, 0x100
	s_waitcnt lgkmcnt(0)
	v_lshl_or_b32 v7, v7, 16, v9
	v_ashrrev_i32_e32 v9, 31, v8
	v_lshl_add_u64 v[8:9], v[8:9], 0, s[18:19]
	v_lshlrev_b64 v[8:9], 7, v[8:9]
	v_lshl_add_u64 v[8:9], s[4:5], 0, v[8:9]
	v_lshl_add_u64 v[8:9], v[8:9], 0, v[198:199]
	v_lshl_add_u64 v[10:11], v[8:9], 0, s[80:81]
	v_add_co_u32_e32 v8, vcc, 0x35e00000, v8
	s_cmpk_eq_i32 s2, 0x800
	s_nop 0
	v_addc_co_u32_e32 v9, vcc, 0, v9, vcc
	global_store_dwordx4 v[8:9], v[0:3], off
	global_store_dwordx4 v[10:11], v[4:7], off offset:16
	s_barrier
	s_cbranch_scc0 .LBB0_291

; DI void attn_item(const Params& p, int item, LAS unsigned char* lds, int tid) {
;     ...
;             const bool sel0 = ((msk[0] >> kt) & 1ull) != 0ull, sel1 = ((msk[1] >> kt) & 1ull) != 0ull;
;             const float bias0 = (br || sel0) ? 0.f : -1e30f, bias1 = (br || sel1) ? 0.f : -1e30f;
;             const bool act0 = br || (__builtin_amdgcn_ballot_w64(sel0) != 0ull), act1 = br || (__builtin_amdgcn_ballot_w64(sel1) != 0ull);
;             const bool edge = (kt == tile) || (br && kt == tile - 8);
.Latt_nostag:
	s_lshl_b64 s[8:9], 1, s54
	s_cmp_lg_u32 s84, 0
	v_and_b32_e32 v113, s9, v205
	v_and_b32_e32 v112, s8, v204
	s_cselect_b64 s[52:53], -1, 0
	s_cmp_eq_u32 s84, 0
	s_mov_b32 s10, s24
	s_mov_b32 s61, s6
	v_cmp_ne_u64_e64 s[6:7], 0, v[112:113]
	s_cselect_b64 s[48:49], -1, 0
	s_and_b64 vcc, exec, s[52:53]
	s_mov_b64 s[24:25], -1
	s_cbranch_vccnz .LBB0_341
	s_cmp_lg_u64 s[6:7], 0
	s_cselect_b64 s[24:25], -1, 0
.LBB0_341:
	v_and_b32_e32 v113, s9, v207
	v_and_b32_e32 v112, s8, v206
	s_mov_b64 s[22:23], -1
	v_cmp_ne_u64_e64 s[8:9], 0, v[112:113]
	s_andn2_b64 vcc, exec, s[48:49]
	s_mov_b64 s[48:49], -1
	s_cbranch_vccnz .LBB0_343
	s_cmp_lg_u64 s[8:9], 0
	s_cselect_b64 s[48:49], -1, 0
